# attention MFMA blocks: exact counted lgkmcnt waits per MFMA instead of lgkmcnt(0); DA K-fragment reads issued before V reads
# speedup vs baseline: 1.0039x; 1.0035x over previous
.LBB0_599:
	s_mov_b32 s75, s74
	s_mov_b32 s74, s0
	v_add_u32_e32 v238, s74, v193
	ds_read_b128 v[82:85], v188 offset:40960
	ds_read_b128 v[210:213], v188 offset:45056
	ds_read_b128 v[214:217], v189 offset:40960
	ds_read_b128 v[218:221], v189 offset:45056
	ds_read_b128 v[222:225], v190 offset:40960
	ds_read_b128 v[226:229], v190 offset:45056
	ds_read_b128 v[230:233], v191 offset:40960
	ds_read_b128 v[234:237], v191 offset:45056
	ds_read_b64_tr_b16 v[194:195], v238 offset:0
	ds_read_b64_tr_b16 v[196:197], v238 offset:0x800
	ds_read_b64_tr_b16 v[198:199], v238 offset:0x1000
	ds_read_b64_tr_b16 v[200:201], v238 offset:0x1800
	s_waitcnt lgkmcnt(11)
	v_mfma_f32_32x32x16_bf16 v[98:113], v[82:85], v[126:129], v[66:81]
	s_waitcnt lgkmcnt(10)
	v_mfma_f32_32x32x16_bf16 v[82:97], v[210:213], v[126:129], v[66:81]
	ds_read_b64_tr_b16 v[202:203], v238 offset:0x2000
	ds_read_b64_tr_b16 v[204:205], v238 offset:0x2800
	ds_read_b64_tr_b16 v[206:207], v238 offset:0x3000
	ds_read_b64_tr_b16 v[208:209], v238 offset:0x3800
	s_waitcnt lgkmcnt(13)
	v_mfma_f32_32x32x16_bf16 v[98:113], v[214:217], v[122:125], v[98:113]
	s_waitcnt lgkmcnt(12)
	v_mfma_f32_32x32x16_bf16 v[82:97], v[218:221], v[122:125], v[82:97]
	s_waitcnt lgkmcnt(11)
	v_mfma_f32_32x32x16_bf16 v[98:113], v[222:225], v[118:121], v[98:113]
	s_waitcnt lgkmcnt(10)
	v_mfma_f32_32x32x16_bf16 v[82:97], v[226:229], v[118:121], v[82:97]
	s_waitcnt lgkmcnt(9)
	v_mfma_f32_32x32x16_bf16 v[98:113], v[230:233], v[114:117], v[98:113]
	s_waitcnt lgkmcnt(8)
	v_mfma_f32_32x32x16_bf16 v[82:97], v[234:237], v[114:117], v[82:97]
	ds_read_b64_tr_b16 v[210:211], v238 offset:0x200
	ds_read_b64_tr_b16 v[212:213], v238 offset:0xa00
	ds_read_b64_tr_b16 v[214:215], v238 offset:0x1200
	ds_read_b64_tr_b16 v[216:217], v238 offset:0x1a00
	ds_read_b64_tr_b16 v[218:219], v238 offset:0x2200
	ds_read_b64_tr_b16 v[220:221], v238 offset:0x2a00
	ds_read_b64_tr_b16 v[222:223], v238 offset:0x3200
	ds_read_b64_tr_b16 v[224:225], v238 offset:0x3a00
	s_waitcnt lgkmcnt(14)
	v_mfma_f32_32x32x16_bf16 v[50:65], v[142:145], v[194:197], v[50:65]
	s_waitcnt lgkmcnt(12)
	v_mfma_f32_32x32x16_bf16 v[50:65], v[138:141], v[198:201], v[50:65]
	s_waitcnt lgkmcnt(10)
	v_mfma_f32_32x32x16_bf16 v[50:65], v[134:137], v[202:205], v[50:65]
	s_waitcnt lgkmcnt(8)
	v_mfma_f32_32x32x16_bf16 v[50:65], v[130:133], v[206:209], v[50:65]
	ds_read_b64_tr_b16 v[194:195], v238 offset:0x400
	ds_read_b64_tr_b16 v[196:197], v238 offset:0xc00
	ds_read_b64_tr_b16 v[198:199], v238 offset:0x1400
	ds_read_b64_tr_b16 v[200:201], v238 offset:0x1c00
	ds_read_b64_tr_b16 v[202:203], v238 offset:0x2400
	ds_read_b64_tr_b16 v[204:205], v238 offset:0x2c00
	ds_read_b64_tr_b16 v[206:207], v238 offset:0x3400
	ds_read_b64_tr_b16 v[208:209], v238 offset:0x3c00
	s_waitcnt lgkmcnt(14)
	v_mfma_f32_32x32x16_bf16 v[34:49], v[142:145], v[210:213], v[34:49]
	s_waitcnt lgkmcnt(12)
	v_mfma_f32_32x32x16_bf16 v[34:49], v[138:141], v[214:217], v[34:49]
	s_waitcnt lgkmcnt(10)
	v_mfma_f32_32x32x16_bf16 v[34:49], v[134:137], v[218:221], v[34:49]
	s_waitcnt lgkmcnt(8)
	v_mfma_f32_32x32x16_bf16 v[34:49], v[130:133], v[222:225], v[34:49]
	ds_read_b64_tr_b16 v[210:211], v238 offset:0x600
	ds_read_b64_tr_b16 v[212:213], v238 offset:0xe00
	ds_read_b64_tr_b16 v[214:215], v238 offset:0x1600
	ds_read_b64_tr_b16 v[216:217], v238 offset:0x1e00
	ds_read_b64_tr_b16 v[218:219], v238 offset:0x2600
	ds_read_b64_tr_b16 v[220:221], v238 offset:0x2e00
	ds_read_b64_tr_b16 v[222:223], v238 offset:0x3600
	ds_read_b64_tr_b16 v[224:225], v238 offset:0x3e00
	s_waitcnt lgkmcnt(14)
	v_mfma_f32_32x32x16_bf16 v[18:33], v[142:145], v[194:197], v[18:33]
	s_waitcnt lgkmcnt(12)
	v_mfma_f32_32x32x16_bf16 v[18:33], v[138:141], v[198:201], v[18:33]
	s_waitcnt lgkmcnt(10)
	v_mfma_f32_32x32x16_bf16 v[18:33], v[134:137], v[202:205], v[18:33]
	s_waitcnt lgkmcnt(8)
	v_mfma_f32_32x32x16_bf16 v[18:33], v[130:133], v[206:209], v[18:33]
	s_waitcnt lgkmcnt(6)
	v_mfma_f32_32x32x16_bf16 v[2:17], v[142:145], v[210:213], v[2:17]
	s_waitcnt lgkmcnt(4)
	v_mfma_f32_32x32x16_bf16 v[2:17], v[138:141], v[214:217], v[2:17]
	s_waitcnt lgkmcnt(2)
	v_mfma_f32_32x32x16_bf16 v[2:17], v[134:137], v[218:221], v[2:17]
	s_waitcnt lgkmcnt(0)
	v_mfma_f32_32x32x16_bf16 v[2:17], v[130:133], v[222:225], v[2:17]
	s_and_b64 vcc, exec, s[6:7]
	s_cbranch_vccnz .LBB0_601
	s_waitcnt vmcnt(1)

.LBB0_612:
	s_barrier
	v_add_u32_e32 v197, s75, v193
	ds_read_b128 v[82:85], v188 offset:32768
	ds_read_b128 v[214:217], v188 offset:36864
	ds_read_b128 v[218:221], v189 offset:32768
	ds_read_b128 v[222:225], v189 offset:36864
	ds_read_b128 v[226:229], v190 offset:32768
	ds_read_b128 v[230:233], v190 offset:36864
	ds_read_b128 v[234:237], v191 offset:32768
	ds_read_b128 v[238:241], v191 offset:36864
	ds_read_b64_tr_b16 v[198:199], v197 offset:0
	ds_read_b64_tr_b16 v[200:201], v197 offset:0x800
	ds_read_b64_tr_b16 v[202:203], v197 offset:0x1000
	ds_read_b64_tr_b16 v[204:205], v197 offset:0x1800
	s_waitcnt lgkmcnt(11)
	v_mfma_f32_32x32x16_bf16 v[98:113], v[82:85], v[126:129], v[66:81]
	s_waitcnt lgkmcnt(10)
	v_mfma_f32_32x32x16_bf16 v[82:97], v[214:217], v[126:129], v[66:81]
	ds_read_b64_tr_b16 v[206:207], v197 offset:0x2000
	ds_read_b64_tr_b16 v[208:209], v197 offset:0x2800
	ds_read_b64_tr_b16 v[210:211], v197 offset:0x3000
	ds_read_b64_tr_b16 v[212:213], v197 offset:0x3800
	s_waitcnt lgkmcnt(13)
	v_mfma_f32_32x32x16_bf16 v[98:113], v[218:221], v[122:125], v[98:113]
	s_waitcnt lgkmcnt(12)
	v_mfma_f32_32x32x16_bf16 v[82:97], v[222:225], v[122:125], v[82:97]
	s_waitcnt lgkmcnt(11)
	v_mfma_f32_32x32x16_bf16 v[98:113], v[226:229], v[118:121], v[98:113]
	s_waitcnt lgkmcnt(10)
	v_mfma_f32_32x32x16_bf16 v[82:97], v[230:233], v[118:121], v[82:97]
	s_waitcnt lgkmcnt(9)
	v_mfma_f32_32x32x16_bf16 v[98:113], v[234:237], v[114:117], v[98:113]
	s_waitcnt lgkmcnt(8)
	v_mfma_f32_32x32x16_bf16 v[82:97], v[238:241], v[114:117], v[82:97]
	ds_read_b64_tr_b16 v[214:215], v197 offset:0x200
	ds_read_b64_tr_b16 v[216:217], v197 offset:0xa00
	ds_read_b64_tr_b16 v[218:219], v197 offset:0x1200
	ds_read_b64_tr_b16 v[220:221], v197 offset:0x1a00
	ds_read_b64_tr_b16 v[222:223], v197 offset:0x2200
	ds_read_b64_tr_b16 v[224:225], v197 offset:0x2a00
	ds_read_b64_tr_b16 v[226:227], v197 offset:0x3200
	ds_read_b64_tr_b16 v[228:229], v197 offset:0x3a00
	s_waitcnt lgkmcnt(14)
	v_mfma_f32_32x32x16_bf16 v[50:65], v[142:145], v[198:201], v[50:65]
	s_waitcnt lgkmcnt(12)
	v_mfma_f32_32x32x16_bf16 v[50:65], v[138:141], v[202:205], v[50:65]
	s_waitcnt lgkmcnt(10)
	v_mfma_f32_32x32x16_bf16 v[50:65], v[134:137], v[206:209], v[50:65]
	s_waitcnt lgkmcnt(8)
	v_mfma_f32_32x32x16_bf16 v[50:65], v[130:133], v[210:213], v[50:65]
	ds_read_b64_tr_b16 v[198:199], v197 offset:0x400
	ds_read_b64_tr_b16 v[200:201], v197 offset:0xc00
	ds_read_b64_tr_b16 v[202:203], v197 offset:0x1400
	ds_read_b64_tr_b16 v[204:205], v197 offset:0x1c00
	ds_read_b64_tr_b16 v[206:207], v197 offset:0x2400
	ds_read_b64_tr_b16 v[208:209], v197 offset:0x2c00
	ds_read_b64_tr_b16 v[210:211], v197 offset:0x3400
	ds_read_b64_tr_b16 v[212:213], v197 offset:0x3c00
	s_waitcnt lgkmcnt(14)
	v_mfma_f32_32x32x16_bf16 v[34:49], v[142:145], v[214:217], v[34:49]
	s_waitcnt lgkmcnt(12)
	v_mfma_f32_32x32x16_bf16 v[34:49], v[138:141], v[218:221], v[34:49]
	s_waitcnt lgkmcnt(10)
	v_mfma_f32_32x32x16_bf16 v[34:49], v[134:137], v[222:225], v[34:49]
	s_waitcnt lgkmcnt(8)
	v_mfma_f32_32x32x16_bf16 v[34:49], v[130:133], v[226:229], v[34:49]
	ds_read_b64_tr_b16 v[214:215], v197 offset:0x600
	ds_read_b64_tr_b16 v[216:217], v197 offset:0xe00
	ds_read_b64_tr_b16 v[218:219], v197 offset:0x1600
	ds_read_b64_tr_b16 v[220:221], v197 offset:0x1e00
	ds_read_b64_tr_b16 v[222:223], v197 offset:0x2600
	ds_read_b64_tr_b16 v[224:225], v197 offset:0x2e00
	ds_read_b64_tr_b16 v[226:227], v197 offset:0x3600
	ds_read_b64_tr_b16 v[228:229], v197 offset:0x3e00
	s_waitcnt lgkmcnt(14)
	v_mfma_f32_32x32x16_bf16 v[18:33], v[142:145], v[198:201], v[18:33]
	s_waitcnt lgkmcnt(12)
	v_mfma_f32_32x32x16_bf16 v[18:33], v[138:141], v[202:205], v[18:33]
	s_waitcnt lgkmcnt(10)
	v_mfma_f32_32x32x16_bf16 v[18:33], v[134:137], v[206:209], v[18:33]
	s_waitcnt lgkmcnt(8)
	v_mfma_f32_32x32x16_bf16 v[18:33], v[130:133], v[210:213], v[18:33]
	s_waitcnt lgkmcnt(6)
	v_mfma_f32_32x32x16_bf16 v[2:17], v[142:145], v[214:217], v[2:17]
	s_waitcnt lgkmcnt(4)
	v_mfma_f32_32x32x16_bf16 v[2:17], v[138:141], v[218:221], v[2:17]
	s_waitcnt lgkmcnt(2)
	v_mfma_f32_32x32x16_bf16 v[2:17], v[134:137], v[222:225], v[2:17]
	s_waitcnt lgkmcnt(0)
	v_mfma_f32_32x32x16_bf16 v[2:17], v[130:133], v[226:229], v[2:17]
	s_and_b64 vcc, exec, s[6:7]
	s_cbranch_vccnz .LBB0_614
	s_waitcnt vmcnt(1)

.LBB0_666:
	v_add_u32_e32 v189, v187, v160
	v_add_u32_e32 v190, v187, v162
	v_add_u32_e32 v191, v187, v164
	v_add_u32_e32 v192, v187, v166
	ds_read_b128 v[66:69], v189 offset:16384
	ds_read_b128 v[70:73], v189 offset:24576
	ds_read_b128 v[194:197], v190 offset:16384
	ds_read_b128 v[198:201], v190 offset:24576
	ds_read_b128 v[202:205], v191 offset:16384
	ds_read_b128 v[206:209], v191 offset:24576
	ds_read_b128 v[210:213], v192 offset:16384
	ds_read_b128 v[214:217], v192 offset:24576
	s_mov_b32 s12, s94
	s_mov_b32 s94, s8
	v_add_u32_e32 v250, s94, v185
	s_waitcnt lgkmcnt(7)
	v_mfma_f32_32x32x16_bf16 v[82:97], v[66:69], v[114:117], 0
	s_waitcnt lgkmcnt(6)
	v_mfma_f32_32x32x16_bf16 v[66:81], v[70:73], v[114:117], 0
	s_waitcnt lgkmcnt(5)
	v_mfma_f32_32x32x16_bf16 v[82:97], v[194:197], v[110:113], v[82:97]
	s_waitcnt lgkmcnt(4)
	v_mfma_f32_32x32x16_bf16 v[66:81], v[198:201], v[110:113], v[66:81]
	v_add_u32_e32 v193, v187, v168
	v_add_u32_e32 v194, v187, v170
	ds_read_b128 v[198:201], v193 offset:24576
	ds_read_b128 v[218:221], v194 offset:16384
	ds_read_b128 v[222:225], v194 offset:24576
	ds_read_b128 v[226:229], v193 offset:16384
	ds_read_b128 v[230:233], v159
	s_waitcnt lgkmcnt(8)
	v_mfma_f32_32x32x16_bf16 v[82:97], v[202:205], v[106:109], v[82:97]
	s_waitcnt lgkmcnt(7)
	v_mfma_f32_32x32x16_bf16 v[66:81], v[206:209], v[106:109], v[66:81]
	s_waitcnt lgkmcnt(6)
	v_mfma_f32_32x32x16_bf16 v[82:97], v[210:213], v[102:105], v[82:97]
	s_waitcnt lgkmcnt(5)
	v_mfma_f32_32x32x16_bf16 v[66:81], v[214:217], v[102:105], v[66:81]
	v_add_u32_e32 v195, v187, v172
	v_add_u32_e32 v196, v187, v174
	ds_read_b128 v[202:205], v195 offset:16384
	ds_read_b128 v[206:209], v195 offset:24576
	ds_read_b128 v[210:213], v196 offset:16384
	ds_read_b128 v[214:217], v196 offset:24576
	ds_read_b128 v[234:237], v159 offset:1024
	ds_read_b128 v[238:241], v159 offset:2048
	s_waitcnt lgkmcnt(7)
	v_mfma_f32_32x32x16_bf16 v[82:97], v[226:229], v[98:101], v[82:97]
	v_mfma_f32_32x32x16_bf16 v[66:81], v[198:201], v[98:101], v[66:81]
	s_waitcnt lgkmcnt(6)
	v_mfma_f32_32x32x16_bf16 v[82:97], v[218:221], v[230:233], v[82:97]
	v_mfma_f32_32x32x16_bf16 v[66:81], v[222:225], v[230:233], v[66:81]
	v_add_u32_e32 v197, v188, v177
	v_add_u32_e32 v198, v188, v179
	ds_read_b128 v[218:221], v197 offset:40960
	ds_read_b128 v[222:225], v197 offset:45056
	ds_read_b128 v[226:229], v198 offset:40960
	ds_read_b128 v[230:233], v198 offset:45056
	ds_read_b128 v[242:245], v159 offset:3072
	ds_read_b128 v[246:249], v159 offset:4096
	s_waitcnt lgkmcnt(7)
	v_mfma_f32_32x32x16_bf16 v[82:97], v[202:205], v[234:237], v[82:97]
	v_mfma_f32_32x32x16_bf16 v[66:81], v[206:209], v[234:237], v[66:81]
	s_waitcnt lgkmcnt(6)
	v_mfma_f32_32x32x16_bf16 v[82:97], v[210:213], v[238:241], v[82:97]
	v_mfma_f32_32x32x16_bf16 v[66:81], v[214:217], v[238:241], v[66:81]
	v_add_u32_e32 v199, v188, v181
	v_add_u32_e32 v200, v188, v183
	ds_read_b128 v[202:205], v199 offset:40960
	ds_read_b128 v[206:209], v199 offset:45056
	ds_read_b128 v[210:213], v200 offset:40960
	ds_read_b128 v[214:217], v200 offset:45056
	ds_read_b128 v[234:237], v159 offset:5120
	ds_read_b128 v[238:241], v159 offset:6144
	s_waitcnt lgkmcnt(7)
	v_mfma_f32_32x32x16_bf16 v[82:97], v[218:221], v[242:245], v[82:97]
	v_mfma_f32_32x32x16_bf16 v[66:81], v[222:225], v[242:245], v[66:81]
	s_waitcnt lgkmcnt(6)
	v_mfma_f32_32x32x16_bf16 v[82:97], v[226:229], v[246:249], v[82:97]
	v_mfma_f32_32x32x16_bf16 v[66:81], v[230:233], v[246:249], v[66:81]
	s_waitcnt lgkmcnt(1)
	v_mfma_f32_32x32x16_bf16 v[82:97], v[202:205], v[234:237], v[82:97]
	v_mfma_f32_32x32x16_bf16 v[66:81], v[206:209], v[234:237], v[66:81]
	s_waitcnt lgkmcnt(0)
	v_mfma_f32_32x32x16_bf16 v[82:97], v[210:213], v[238:241], v[82:97]
	v_mfma_f32_32x32x16_bf16 v[66:81], v[214:217], v[238:241], v[66:81]
	ds_read_b64_tr_b16 v[202:203], v250 offset:0
	ds_read_b64_tr_b16 v[204:205], v250 offset:0x800
	ds_read_b64_tr_b16 v[206:207], v250 offset:0x1000
	ds_read_b64_tr_b16 v[208:209], v250 offset:0x1800
	ds_read_b64_tr_b16 v[210:211], v250 offset:0x2000
	ds_read_b64_tr_b16 v[212:213], v250 offset:0x2800
	ds_read_b64_tr_b16 v[214:215], v250 offset:0x3000
	ds_read_b64_tr_b16 v[216:217], v250 offset:0x3800
	ds_read_b64_tr_b16 v[218:219], v250 offset:0x200
	ds_read_b64_tr_b16 v[220:221], v250 offset:0xa00
	ds_read_b64_tr_b16 v[222:223], v250 offset:0x1200
	ds_read_b64_tr_b16 v[224:225], v250 offset:0x1a00
	ds_read_b64_tr_b16 v[226:227], v250 offset:0x2200
	ds_read_b64_tr_b16 v[228:229], v250 offset:0x2a00
	ds_read_b64_tr_b16 v[230:231], v250 offset:0x3200
	ds_read_b64_tr_b16 v[232:233], v250 offset:0x3a00
	s_nop 0
	s_waitcnt lgkmcnt(14)
	v_mfma_f32_32x32x16_bf16 v[50:65], v[130:133], v[202:205], v[50:65]
	s_waitcnt lgkmcnt(12)
	v_mfma_f32_32x32x16_bf16 v[50:65], v[126:129], v[206:209], v[50:65]
	s_waitcnt lgkmcnt(10)
	v_mfma_f32_32x32x16_bf16 v[50:65], v[122:125], v[210:213], v[50:65]
	s_waitcnt lgkmcnt(8)
	v_mfma_f32_32x32x16_bf16 v[50:65], v[118:121], v[214:217], v[50:65]
	ds_read_b64_tr_b16 v[202:203], v250 offset:0x400
	ds_read_b64_tr_b16 v[204:205], v250 offset:0xc00
	ds_read_b64_tr_b16 v[206:207], v250 offset:0x1400
	ds_read_b64_tr_b16 v[208:209], v250 offset:0x1c00
	ds_read_b64_tr_b16 v[210:211], v250 offset:0x2400
	ds_read_b64_tr_b16 v[212:213], v250 offset:0x2c00
	ds_read_b64_tr_b16 v[214:215], v250 offset:0x3400
	ds_read_b64_tr_b16 v[216:217], v250 offset:0x3c00
	s_waitcnt lgkmcnt(14)
	v_mfma_f32_32x32x16_bf16 v[34:49], v[130:133], v[218:221], v[34:49]
	s_waitcnt lgkmcnt(12)
	v_mfma_f32_32x32x16_bf16 v[34:49], v[126:129], v[222:225], v[34:49]
	s_waitcnt lgkmcnt(10)
	v_mfma_f32_32x32x16_bf16 v[34:49], v[122:125], v[226:229], v[34:49]
	s_waitcnt lgkmcnt(8)
	v_mfma_f32_32x32x16_bf16 v[34:49], v[118:121], v[230:233], v[34:49]
	ds_read_b64_tr_b16 v[218:219], v250 offset:0x600
	ds_read_b64_tr_b16 v[220:221], v250 offset:0xe00
	ds_read_b64_tr_b16 v[222:223], v250 offset:0x1600
	ds_read_b64_tr_b16 v[224:225], v250 offset:0x1e00
	ds_read_b64_tr_b16 v[226:227], v250 offset:0x2600
	ds_read_b64_tr_b16 v[228:229], v250 offset:0x2e00
	ds_read_b64_tr_b16 v[230:231], v250 offset:0x3600
	ds_read_b64_tr_b16 v[232:233], v250 offset:0x3e00
	s_waitcnt lgkmcnt(14)
	v_mfma_f32_32x32x16_bf16 v[18:33], v[130:133], v[202:205], v[18:33]
	s_waitcnt lgkmcnt(12)
	v_mfma_f32_32x32x16_bf16 v[18:33], v[126:129], v[206:209], v[18:33]
	s_waitcnt lgkmcnt(10)
	v_mfma_f32_32x32x16_bf16 v[18:33], v[122:125], v[210:213], v[18:33]
	s_waitcnt lgkmcnt(8)
	v_mfma_f32_32x32x16_bf16 v[18:33], v[118:121], v[214:217], v[18:33]
	s_waitcnt lgkmcnt(6)
	v_mfma_f32_32x32x16_bf16 v[2:17], v[130:133], v[218:221], v[2:17]
	s_waitcnt lgkmcnt(4)
	v_mfma_f32_32x32x16_bf16 v[2:17], v[126:129], v[222:225], v[2:17]
	s_waitcnt lgkmcnt(2)
	v_mfma_f32_32x32x16_bf16 v[2:17], v[122:125], v[226:229], v[2:17]
	s_waitcnt lgkmcnt(0)
	v_mfma_f32_32x32x16_bf16 v[2:17], v[118:121], v[230:233], v[2:17]
	s_and_b64 vcc, exec, s[6:7]
	s_cbranch_vccnz .LBB0_668
	s_waitcnt vmcnt(0)

.LBB0_678:
	s_barrier
	ds_read_b128 v[66:69], v161
	ds_read_b128 v[70:73], v161 offset:8192
	ds_read_b128 v[204:207], v163
	ds_read_b128 v[208:211], v163 offset:8192
	ds_read_b128 v[212:215], v165
	ds_read_b128 v[216:219], v165 offset:8192
	ds_read_b128 v[220:223], v167
	ds_read_b128 v[224:227], v167 offset:8192
	v_add_u32_e32 v252, s12, v185
	s_waitcnt lgkmcnt(7)
	v_mfma_f32_32x32x16_bf16 v[82:97], v[66:69], v[114:117], 0
	s_waitcnt lgkmcnt(6)
	v_mfma_f32_32x32x16_bf16 v[66:81], v[70:73], v[114:117], 0
	s_waitcnt lgkmcnt(5)
	v_mfma_f32_32x32x16_bf16 v[82:97], v[204:207], v[110:113], v[82:97]
	s_waitcnt lgkmcnt(4)
	v_mfma_f32_32x32x16_bf16 v[66:81], v[208:211], v[110:113], v[66:81]
	ds_read_b128 v[204:207], v169 offset:8192
	ds_read_b128 v[208:211], v171
	ds_read_b128 v[228:231], v171 offset:8192
	ds_read_b128 v[232:235], v169
	ds_read_b128 v[236:239], v159
	s_waitcnt lgkmcnt(8)
	v_mfma_f32_32x32x16_bf16 v[82:97], v[212:215], v[106:109], v[82:97]
	s_waitcnt lgkmcnt(7)
	v_mfma_f32_32x32x16_bf16 v[66:81], v[216:219], v[106:109], v[66:81]
	s_waitcnt lgkmcnt(6)
	v_mfma_f32_32x32x16_bf16 v[82:97], v[220:223], v[102:105], v[82:97]
	s_waitcnt lgkmcnt(5)
	v_mfma_f32_32x32x16_bf16 v[66:81], v[224:227], v[102:105], v[66:81]
	ds_read_b128 v[212:215], v173
	ds_read_b128 v[216:219], v173 offset:8192
	ds_read_b128 v[220:223], v175
	ds_read_b128 v[224:227], v175 offset:8192
	ds_read_b128 v[240:243], v159 offset:1024
	ds_read_b128 v[244:247], v159 offset:2048
	s_waitcnt lgkmcnt(7)
	v_mfma_f32_32x32x16_bf16 v[82:97], v[232:235], v[98:101], v[82:97]
	v_mfma_f32_32x32x16_bf16 v[66:81], v[204:207], v[98:101], v[66:81]
	s_waitcnt lgkmcnt(6)
	v_mfma_f32_32x32x16_bf16 v[82:97], v[208:211], v[236:239], v[82:97]
	v_mfma_f32_32x32x16_bf16 v[66:81], v[228:231], v[236:239], v[66:81]
	ds_read_b128 v[204:207], v178 offset:32768
	ds_read_b128 v[208:211], v178 offset:36864
	ds_read_b128 v[228:231], v180 offset:32768
	ds_read_b128 v[232:235], v180 offset:36864
	ds_read_b128 v[236:239], v159 offset:3072
	ds_read_b128 v[248:251], v159 offset:4096
	s_waitcnt lgkmcnt(7)
	v_mfma_f32_32x32x16_bf16 v[82:97], v[212:215], v[240:243], v[82:97]
	v_mfma_f32_32x32x16_bf16 v[66:81], v[216:219], v[240:243], v[66:81]
	s_waitcnt lgkmcnt(6)
	v_mfma_f32_32x32x16_bf16 v[82:97], v[220:223], v[244:247], v[82:97]
	v_mfma_f32_32x32x16_bf16 v[66:81], v[224:227], v[244:247], v[66:81]
	ds_read_b128 v[212:215], v182 offset:32768
	ds_read_b128 v[216:219], v182 offset:36864
	ds_read_b128 v[220:223], v184 offset:32768
	ds_read_b128 v[224:227], v184 offset:36864
	ds_read_b128 v[240:243], v159 offset:5120
	ds_read_b128 v[244:247], v159 offset:6144
	s_waitcnt lgkmcnt(7)
	v_mfma_f32_32x32x16_bf16 v[82:97], v[204:207], v[236:239], v[82:97]
	v_mfma_f32_32x32x16_bf16 v[66:81], v[208:211], v[236:239], v[66:81]
	s_waitcnt lgkmcnt(6)
	v_mfma_f32_32x32x16_bf16 v[82:97], v[228:231], v[248:251], v[82:97]
	v_mfma_f32_32x32x16_bf16 v[66:81], v[232:235], v[248:251], v[66:81]
	s_waitcnt lgkmcnt(1)
	v_mfma_f32_32x32x16_bf16 v[82:97], v[212:215], v[240:243], v[82:97]
	v_mfma_f32_32x32x16_bf16 v[66:81], v[216:219], v[240:243], v[66:81]
	s_waitcnt lgkmcnt(0)
	v_mfma_f32_32x32x16_bf16 v[82:97], v[220:223], v[244:247], v[82:97]
	v_mfma_f32_32x32x16_bf16 v[66:81], v[224:227], v[244:247], v[66:81]
	ds_read_b64_tr_b16 v[204:205], v252 offset:0
	ds_read_b64_tr_b16 v[206:207], v252 offset:0x800
	ds_read_b64_tr_b16 v[208:209], v252 offset:0x1000
	ds_read_b64_tr_b16 v[210:211], v252 offset:0x1800
	ds_read_b64_tr_b16 v[212:213], v252 offset:0x2000
	ds_read_b64_tr_b16 v[214:215], v252 offset:0x2800
	ds_read_b64_tr_b16 v[216:217], v252 offset:0x3000
	ds_read_b64_tr_b16 v[218:219], v252 offset:0x3800
	ds_read_b64_tr_b16 v[220:221], v252 offset:0x200
	ds_read_b64_tr_b16 v[222:223], v252 offset:0xa00
	ds_read_b64_tr_b16 v[224:225], v252 offset:0x1200
	ds_read_b64_tr_b16 v[226:227], v252 offset:0x1a00
	ds_read_b64_tr_b16 v[228:229], v252 offset:0x2200
	ds_read_b64_tr_b16 v[230:231], v252 offset:0x2a00
	ds_read_b64_tr_b16 v[232:233], v252 offset:0x3200
	ds_read_b64_tr_b16 v[234:235], v252 offset:0x3a00
	s_nop 0
	s_waitcnt lgkmcnt(14)
	v_mfma_f32_32x32x16_bf16 v[50:65], v[130:133], v[204:207], v[50:65]
	s_waitcnt lgkmcnt(12)
	v_mfma_f32_32x32x16_bf16 v[50:65], v[126:129], v[208:211], v[50:65]
	s_waitcnt lgkmcnt(10)
	v_mfma_f32_32x32x16_bf16 v[50:65], v[122:125], v[212:215], v[50:65]
	s_waitcnt lgkmcnt(8)
	v_mfma_f32_32x32x16_bf16 v[50:65], v[118:121], v[216:219], v[50:65]
	ds_read_b64_tr_b16 v[204:205], v252 offset:0x400
	ds_read_b64_tr_b16 v[206:207], v252 offset:0xc00
	ds_read_b64_tr_b16 v[208:209], v252 offset:0x1400
	ds_read_b64_tr_b16 v[210:211], v252 offset:0x1c00
	ds_read_b64_tr_b16 v[212:213], v252 offset:0x2400
	ds_read_b64_tr_b16 v[214:215], v252 offset:0x2c00
	ds_read_b64_tr_b16 v[216:217], v252 offset:0x3400
	ds_read_b64_tr_b16 v[218:219], v252 offset:0x3c00
	s_waitcnt lgkmcnt(14)
	v_mfma_f32_32x32x16_bf16 v[34:49], v[130:133], v[220:223], v[34:49]
	s_waitcnt lgkmcnt(12)
	v_mfma_f32_32x32x16_bf16 v[34:49], v[126:129], v[224:227], v[34:49]
	s_waitcnt lgkmcnt(10)
	v_mfma_f32_32x32x16_bf16 v[34:49], v[122:125], v[228:231], v[34:49]
	s_waitcnt lgkmcnt(8)
	v_mfma_f32_32x32x16_bf16 v[34:49], v[118:121], v[232:235], v[34:49]
	ds_read_b64_tr_b16 v[220:221], v252 offset:0x600
	ds_read_b64_tr_b16 v[222:223], v252 offset:0xe00
	ds_read_b64_tr_b16 v[224:225], v252 offset:0x1600
	ds_read_b64_tr_b16 v[226:227], v252 offset:0x1e00
	ds_read_b64_tr_b16 v[228:229], v252 offset:0x2600
	ds_read_b64_tr_b16 v[230:231], v252 offset:0x2e00
	ds_read_b64_tr_b16 v[232:233], v252 offset:0x3600
	ds_read_b64_tr_b16 v[234:235], v252 offset:0x3e00
	s_waitcnt lgkmcnt(14)
	v_mfma_f32_32x32x16_bf16 v[18:33], v[130:133], v[204:207], v[18:33]
	s_waitcnt lgkmcnt(12)
	v_mfma_f32_32x32x16_bf16 v[18:33], v[126:129], v[208:211], v[18:33]
	s_waitcnt lgkmcnt(10)
	v_mfma_f32_32x32x16_bf16 v[18:33], v[122:125], v[212:215], v[18:33]
	s_waitcnt lgkmcnt(8)
	v_mfma_f32_32x32x16_bf16 v[18:33], v[118:121], v[216:219], v[18:33]
	s_waitcnt lgkmcnt(6)
	v_mfma_f32_32x32x16_bf16 v[2:17], v[130:133], v[220:223], v[2:17]
	s_waitcnt lgkmcnt(4)
	v_mfma_f32_32x32x16_bf16 v[2:17], v[126:129], v[224:227], v[2:17]
	s_waitcnt lgkmcnt(2)
	v_mfma_f32_32x32x16_bf16 v[2:17], v[122:125], v[228:231], v[2:17]
	s_waitcnt lgkmcnt(0)
	v_mfma_f32_32x32x16_bf16 v[2:17], v[118:121], v[232:235], v[2:17]
	s_and_b64 vcc, exec, s[6:7]
	s_cbranch_vccnz .LBB0_680
	s_waitcnt vmcnt(0)
